# P0 weight transposition: jobs flattened into one item sequence, hand-written item body (SGPR-base loads, item pipelined across jobs, per-wave row rotation); diff tile-1 prologue overlap
# speedup vs baseline: 1.0921x; 1.0035x over previous
; #define LAS __attribute__((address_space(3)))
; __global__ void __launch_bounds__(NTHREADS, 2) mega_fwd(Args args) {
;     ...
;     const float* x = INP(0); const float* mem = INP(1); const int* positions = (const int*)INP(2);
;     bf16* XH = (bf16*)(ws + A_XH);
;     bf16* QDb = (bf16*)args.out; bf16* KDb = (bf16*)args.out + (size_t)T * 1024;
;     bf16* XN = (bf16*)(ws + A_XN);
;     REP(0) if (IN(0)) {
;         PHASE_IDS;
;         LAS float* scr = (LAS float*)(lds + wave * 8704);
;         for (int job = 0; job < 18; ++job) {
;             const float* W; int K, N, mode = 0; bf16* dst;
;             switch (job) {
;                 case 0: W = INP(4); K = 1024; N = 1184; dst = (bf16*)(ws + W_WIN); break;
;                 case 1: W = INP(10); K = 256; N = 768; dst = (bf16*)(ws + W_WUQ); break;
;                 case 2: W = INP(11); K = 128; N = 1024; dst = (bf16*)(ws + W_WUKV); break;
;                 case 3: W = INP(14); K = 1024; N = 1024; dst = (bf16*)(ws + W_WO0); break;
;                 case 4: W = INP(15); K = 1024; N = 3072; mode = 3; dst = (bf16*)(ws + W_WQKV); break;
;                 case 5: W = INP(20); K = 1024; N = 1024; dst = (bf16*)(ws + W_WDO); break;
;                 case 6: case 7: W = INP(23) + (size_t)(job - 6) * 1024 * 512; K = 1024; N = 512; dst = (bf16*)(ws + W_WMQ) + (size_t)(job - 6) * 512 * 1024; break;
;                 case 8: case 9: W = INP(24) + (size_t)(job - 8) * 1024 * 1024; K = 1024; N = 1024; dst = (bf16*)(ws + W_WMKV) + (size_t)(job - 8) * 1024 * 1024; break;
;                 case 10: case 11: W = INP(27) + (size_t)(job - 10) * 512 * 1024; K = 512; N = 1024; dst = (bf16*)(ws + W_WMO) + (size_t)(job - 10) * 1024 * 512; break;
;                 case 12: case 13: W = INP(29) + (size_t)(job - 12) * 1024 * DFF; K = 1024; N = DFF; mode = 1; dst = (bf16*)(ws + W_WGU) + (size_t)(job - 12) * 5632 * 1024; break;
;                 case 14: case 15: W = INP(30) + (size_t)(job - 14) * 1024 * DFF; K = 1024; N = DFF; mode = 2; dst = (bf16*)(ws + W_WGU) + (size_t)(job - 14) * 5632 * 1024; break;
;                 default: W = INP(31) + (size_t)(job - 16) * DFF * 1024; K = DFF; N = 1024; dst = (bf16*)(ws + W_WD) + (size_t)(job - 16) * 1024 * DFF; break;
;             }
;             const int nitems = (K / 64) * (N / 32);
;             for (int it = gw; it < nitems; it += NGW) transpose_item(W, K, N, dst, mode, scr, it, lane);
.LBB0_17:
	s_load_dwordx4 s[12:15], s[82:83], 0x100
	s_cmp_lt_i32 s58, 1
	s_cselect_b64 s[48:49], -1, 0
	s_cmp_gt_i32 s59, 0
	s_cselect_b64 s[2:3], -1, 0
	s_and_b64 s[2:3], s[48:49], s[2:3]
	s_waitcnt lgkmcnt(0)
	s_mov_b64 s[18:19], s[14:15]
	s_add_u32 s4, s18, 0x1520000
	v_writelane_b32 v252, s4, 6
	s_addc_u32 s4, s19, 0
	v_writelane_b32 v252, s4, 7
	s_add_u32 s4, s18, 0x1320000
	v_writelane_b32 v252, s4, 8
	s_addc_u32 s4, s19, 0
	s_add_u32 s52, s18, 0xf20000
	s_addc_u32 s53, s19, 0
	v_writelane_b32 v252, s4, 9
	s_add_u32 s4, s18, 0xd20000
	v_writelane_b32 v252, s4, 10
	s_addc_u32 s4, s19, 0
	v_writelane_b32 v252, s4, 11
	s_add_u32 s4, s18, 0xb20000
	s_addc_u32 s5, s19, 0
	v_writelane_b32 v252, s4, 12
	s_mov_b64 s[16:17], s[12:13]
	s_load_dwordx2 s[0:1], s[82:83], 0x0
	s_load_dwordx2 s[10:11], s[82:83], 0x8
	s_load_dwordx2 s[6:7], s[82:83], 0x10
	v_writelane_b32 v252, s5, 13
	s_add_u32 s4, s18, 0x520000
	s_addc_u32 s5, s19, 0
	s_add_u32 s78, s18, 0x320000
	s_addc_u32 s79, s19, 0
	s_add_u32 s14, s18, 0x2e0000
	s_addc_u32 s15, s19, 0
	s_add_u32 s16, s18, 0x280000
	v_writelane_b32 v252, s4, 14
	s_addc_u32 s17, s19, 0
	s_nop 0
	v_writelane_b32 v252, s5, 15
	s_add_u32 s4, s18, 0x2b20000
	v_writelane_b32 v252, s4, 16
	s_addc_u32 s4, s19, 0
	v_writelane_b32 v252, s4, 17
	s_add_u32 s4, s82, 0x118
	s_addc_u32 s5, s83, 0
	s_add_u32 s54, s18, 0x3700000
	v_writelane_b32 v252, s4, 18
	s_addc_u32 s55, s19, 0
	s_nop 0
	v_writelane_b32 v252, s5, 19
	s_add_u32 s4, s18, 0x4100000
	s_addc_u32 s5, s19, 0
	v_writelane_b32 v252, s4, 20
	s_andn2_b64 vcc, exec, s[2:3]
	s_nop 0
	v_writelane_b32 v252, s5, 21
	s_mov_b32 s5, 0
	s_cbranch_vccnz .LBB0_102
	v_mov_b32_e32 v17, v212
	s_lshl_b32 s2, s84, 3
	v_readfirstlane_b32 s3, v17
	s_ashr_i32 s3, s3, 6
	v_lshlrev_b32_e32 v1, 3, v17
	s_add_i32 s8, s3, s2
	s_mulk_i32 s3, 0x2200
	v_bfe_u32 v7, v17, 3, 3
	v_and_b32_e32 v8, 56, v1
	s_add_i32 s2, s3, 0
	v_bfe_u32 v0, v17, 5, 1
	v_and_b32_e32 v2, 31, v17
	v_mul_u32_u24_e32 v1, 0x84, v8
	v_lshlrev_b32_e32 v5, 2, v7
	v_and_b32_e32 v4, 63, v17
	v_mov_b32_e32 v3, 0
	v_lshl_add_u32 v6, v2, 2, s2
	s_movk_i32 s9, 0x84
	v_add3_u32 v18, s2, v1, v5
	v_or_b32_e32 v19, 8, v7
	v_or_b32_e32 v20, 16, v7
	v_or_b32_e32 v21, 24, v7
	v_mov_b32_e32 v1, v0
	v_lshlrev_b32_e32 v2, 2, v2
	v_lshlrev_b32_e32 v8, 1, v8
	s_mov_b32 s22, 0
	s_mov_b32 s98, s8
	s_mov_b32 s30, 0
	v_mad_u32_u24 v10, v0, s9, v6
	v_readlane_b32 s12, v252, 18
	v_readlane_b32 s13, v252, 19
	s_load_dword s99, s[12:13], 0x0
	s_waitcnt lgkmcnt(0)
	s_lshl_b32 s99, s99, 3
	s_branch .LBB0_20

; #define LAS __attribute__((address_space(3)))
; __device__ __forceinline__ void transpose_item(const float* W, int K, int N, bf16* WT, int mode, LAS float* scr, int item, int lane) {
;     const int nblk = N / 32, kb = item / nblk, nb = item % nblk, k0 = 64 * kb, n0 = 32 * nb;
;     const int drow0 = (mode == 0) ? n0 : (mode == 3) ? ((n0 < 2048) ? 256 * (n0 >> 8) + 128 * ((n0 >> 5) & 1) + 32 * ((n0 >> 6) & 3) : n0)
; __global__ void __launch_bounds__(NTHREADS, 2) mega_fwd(Args args) {
;     ...
;         for (int job = 0; job < 18; ++job) {
;             const float* W; int K, N, mode = 0; bf16* dst;
;             switch (job) {
;                 case 0: W = INP(4); K = 1024; N = 1184; dst = (bf16*)(ws + W_WIN); break;
;                 case 1: W = INP(10); K = 256; N = 768; dst = (bf16*)(ws + W_WUQ); break;
;                 case 2: W = INP(11); K = 128; N = 1024; dst = (bf16*)(ws + W_WUKV); break;
;                 case 3: W = INP(14); K = 1024; N = 1024; dst = (bf16*)(ws + W_WO0); break;
;                 case 4: W = INP(15); K = 1024; N = 3072; mode = 3; dst = (bf16*)(ws + W_WQKV); break;
;                 case 5: W = INP(20); K = 1024; N = 1024; dst = (bf16*)(ws + W_WDO); break;
;                 case 6: case 7: W = INP(23) + (size_t)(job - 6) * 1024 * 512; K = 1024; N = 512; dst = (bf16*)(ws + W_WMQ) + (size_t)(job - 6) * 512 * 1024; break;
;                 case 8: case 9: W = INP(24) + (size_t)(job - 8) * 1024 * 1024; K = 1024; N = 1024; dst = (bf16*)(ws + W_WMKV) + (size_t)(job - 8) * 1024 * 1024; break;
;                 case 10: case 11: W = INP(27) + (size_t)(job - 10) * 512 * 1024; K = 512; N = 1024; dst = (bf16*)(ws + W_WMO) + (size_t)(job - 10) * 1024 * 512; break;
;                 case 12: case 13: W = INP(29) + (size_t)(job - 12) * 1024 * DFF; K = 1024; N = DFF; mode = 1; dst = (bf16*)(ws + W_WGU) + (size_t)(job - 12) * 5632 * 1024; break;
;                 case 14: case 15: W = INP(30) + (size_t)(job - 14) * 1024 * DFF; K = 1024; N = DFF; mode = 2; dst = (bf16*)(ws + W_WGU) + (size_t)(job - 14) * 5632 * 1024; break;
;                 default: W = INP(31) + (size_t)(job - 16) * DFF * 1024; K = DFF; N = 1024; dst = (bf16*)(ws + W_WD) + (size_t)(job - 16) * 1024 * DFF; break;
;             }
;             const int nitems = (K / 64) * (N / 32);
;             for (int it = gw; it < nitems; it += NGW) transpose_item(W, K, N, dst, mode, scr, it, lane);
.LBB0_63:
	s_lshr_b32 s21, s4, 6
	s_lshr_b32 s20, s2, 5
	s_mul_i32 s21, s21, s20
	s_cmp_ge_i32 s98, s21
	s_cbranch_scc1 .Lp0_skip
	s_waitcnt lgkmcnt(0)
	s_mov_b64 s[44:45], s[12:13]
	s_mov_b64 s[34:35], s[18:19]
	v_cvt_f32_u32_e32 v5, s20
	s_sub_i32 s12, 0, s20
	v_rcp_iflag_f32_e32 v5, v5
	s_nop 0
	v_mul_f32_e32 v5, 0x4f7ffffe, v5
	v_cvt_u32_f32_e32 v5, v5
	s_nop 0
	v_readfirstlane_b32 s13, v5
	s_mul_i32 s12, s12, s13
	s_mul_hi_u32 s12, s13, s12
	s_add_i32 s25, s13, s12
.Lp0_item:
	s_mov_b32 s26, s98
	s_abs_i32 s13, s26
	s_mul_hi_u32 s18, s13, s25
	s_mul_i32 s19, s18, s20
	s_sub_i32 s13, s13, s19
	s_ashr_i32 s12, s26, 31
	s_add_i32 s19, s18, 1
	s_sub_i32 s27, s13, s20
	s_cmp_ge_u32 s13, s20
	s_cselect_b32 s18, s19, s18
	s_cselect_b32 s13, s27, s13
	s_add_i32 s19, s18, 1
	s_cmp_ge_u32 s13, s20
	s_cselect_b32 s13, s19, s18
	s_xor_b32 s13, s13, s12
	s_sub_i32 s19, s13, s12
	s_mul_i32 s12, s19, s20
	s_sub_i32 s28, s26, s12
	s_lshl_b32 s18, s28, 5
	s_cmp_gt_i32 s3, 2
	s_cbranch_scc0 .Lp0_m012
	s_lshl_b32 s13, s28, 7
	s_and_b32 s12, s18, 0xffffff00
	s_and_b32 s13, s13, 0x80
	s_or_b32 s12, s12, s13
	s_lshl_b32 s13, s28, 4
	s_and_b32 s13, s13, 0x60
	s_or_b32 s12, s12, s13
	s_cmp_lt_i32 s28, 64
	s_cselect_b32 s27, s12, s18
	s_branch .Lp0_mdone
.Lp0_m012:
	s_cmp_lg_u32 s3, 0
	s_mov_b32 s27, s18
	s_cbranch_scc0 .Lp0_mdone
	s_lshl_b32 s12, s28, 6
	s_and_b32 s13, s18, 0x60
	s_and_b32 s12, s12, 0xffffff00
	s_or_b32 s13, s13, s23
	s_or_b32 s27, s13, s12
.Lp0_mdone:
	s_lshl_b32 s29, s19, 6
	s_mul_i32 s12, s29, s2
	s_add_i32 s12, s12, s18
	s_lshl_b32 s12, s12, 2
	s_add_u32 s36, s44, s12
	s_addc_u32 s37, s45, 0
	v_mul_u32_u24_e32 v16, s2, v0
	s_lshl_b32 s13, s2, 3
	v_lshl_add_u32 v16, v16, 2, v2
	v_mov_b32_e32 v11, s13
	s_and_b32 s24, s26, 31
	s_cmp_eq_u32 s30, 0
	s_cbranch_scc1 .Lp0_np1
	s_waitcnt vmcnt(0)
	s_mul_i32 s13, s46, 264
	v_add_u32_e32 v54, s13, v10
	ds_write_b32 v54, v22
	s_add_i32 s12, s46, 1
	s_and_b32 s12, s12, 31
	s_mul_i32 s13, s12, 264
	v_add_u32_e32 v55, s13, v10
	ds_write_b32 v55, v23
	s_add_i32 s12, s46, 2
	s_and_b32 s12, s12, 31
	s_mul_i32 s13, s12, 264
	v_add_u32_e32 v56, s13, v10
	ds_write_b32 v56, v24
	s_add_i32 s12, s46, 3
	s_and_b32 s12, s12, 31
	s_mul_i32 s13, s12, 264
	v_add_u32_e32 v57, s13, v10
	ds_write_b32 v57, v25
	s_add_i32 s12, s46, 4
	s_and_b32 s12, s12, 31
	s_mul_i32 s13, s12, 264
	v_add_u32_e32 v58, s13, v10
	ds_write_b32 v58, v26
	s_add_i32 s12, s46, 5
	s_and_b32 s12, s12, 31
	s_mul_i32 s13, s12, 264
	v_add_u32_e32 v59, s13, v10
	ds_write_b32 v59, v27
	s_add_i32 s12, s46, 6
	s_and_b32 s12, s12, 31
	s_mul_i32 s13, s12, 264
	v_add_u32_e32 v60, s13, v10
	ds_write_b32 v60, v28
	s_add_i32 s12, s46, 7
	s_and_b32 s12, s12, 31
	s_mul_i32 s13, s12, 264
	v_add_u32_e32 v61, s13, v10
	ds_write_b32 v61, v29
	s_add_i32 s12, s46, 8
	s_and_b32 s12, s12, 31
	s_mul_i32 s13, s12, 264
	v_add_u32_e32 v54, s13, v10
	ds_write_b32 v54, v30
	s_add_i32 s12, s46, 9
	s_and_b32 s12, s12, 31
	s_mul_i32 s13, s12, 264
	v_add_u32_e32 v55, s13, v10
	ds_write_b32 v55, v31
	s_add_i32 s12, s46, 10
	s_and_b32 s12, s12, 31
	s_mul_i32 s13, s12, 264
	v_add_u32_e32 v56, s13, v10
	ds_write_b32 v56, v32
	s_add_i32 s12, s46, 11
	s_and_b32 s12, s12, 31
	s_mul_i32 s13, s12, 264
	v_add_u32_e32 v57, s13, v10
	ds_write_b32 v57, v33
	s_add_i32 s12, s46, 12
	s_and_b32 s12, s12, 31
	s_mul_i32 s13, s12, 264
	v_add_u32_e32 v58, s13, v10
	ds_write_b32 v58, v34
	s_add_i32 s12, s46, 13
	s_and_b32 s12, s12, 31
	s_mul_i32 s13, s12, 264
	v_add_u32_e32 v59, s13, v10
	ds_write_b32 v59, v35
	s_add_i32 s12, s46, 14
	s_and_b32 s12, s12, 31
	s_mul_i32 s13, s12, 264
	v_add_u32_e32 v60, s13, v10
	ds_write_b32 v60, v36
	s_add_i32 s12, s46, 15
	s_and_b32 s12, s12, 31
	s_mul_i32 s13, s12, 264
	v_add_u32_e32 v61, s13, v10
	ds_write_b32 v61, v37
	s_add_i32 s12, s46, 16
	s_and_b32 s12, s12, 31
	s_mul_i32 s13, s12, 264
	v_add_u32_e32 v54, s13, v10
	ds_write_b32 v54, v38
	s_add_i32 s12, s46, 17
	s_and_b32 s12, s12, 31
	s_mul_i32 s13, s12, 264
	v_add_u32_e32 v55, s13, v10
	ds_write_b32 v55, v39
	s_add_i32 s12, s46, 18
	s_and_b32 s12, s12, 31
	s_mul_i32 s13, s12, 264
	v_add_u32_e32 v56, s13, v10
	ds_write_b32 v56, v40
	s_add_i32 s12, s46, 19
	s_and_b32 s12, s12, 31
	s_mul_i32 s13, s12, 264
	v_add_u32_e32 v57, s13, v10
	ds_write_b32 v57, v41
	s_add_i32 s12, s46, 20
	s_and_b32 s12, s12, 31
	s_mul_i32 s13, s12, 264
	v_add_u32_e32 v58, s13, v10
	ds_write_b32 v58, v42
	s_add_i32 s12, s46, 21
	s_and_b32 s12, s12, 31
	s_mul_i32 s13, s12, 264
	v_add_u32_e32 v59, s13, v10
	ds_write_b32 v59, v43
	s_add_i32 s12, s46, 22
	s_and_b32 s12, s12, 31
	s_mul_i32 s13, s12, 264
	v_add_u32_e32 v60, s13, v10
	ds_write_b32 v60, v44
	s_add_i32 s12, s46, 23
	s_and_b32 s12, s12, 31
	s_mul_i32 s13, s12, 264
	v_add_u32_e32 v61, s13, v10
	ds_write_b32 v61, v45
	s_add_i32 s12, s46, 24
	s_and_b32 s12, s12, 31
	s_mul_i32 s13, s12, 264
	v_add_u32_e32 v54, s13, v10
	ds_write_b32 v54, v46
	s_add_i32 s12, s46, 25
	s_and_b32 s12, s12, 31
	s_mul_i32 s13, s12, 264
	v_add_u32_e32 v55, s13, v10
	ds_write_b32 v55, v47
	s_add_i32 s12, s46, 26
	s_and_b32 s12, s12, 31
	s_mul_i32 s13, s12, 264
	v_add_u32_e32 v56, s13, v10
	ds_write_b32 v56, v48
	s_add_i32 s12, s46, 27
	s_and_b32 s12, s12, 31
	s_mul_i32 s13, s12, 264
	v_add_u32_e32 v57, s13, v10
	ds_write_b32 v57, v49
	s_add_i32 s12, s46, 28
	s_and_b32 s12, s12, 31
	s_mul_i32 s13, s12, 264
	v_add_u32_e32 v58, s13, v10
	ds_write_b32 v58, v50
	s_add_i32 s12, s46, 29
	s_and_b32 s12, s12, 31
	s_mul_i32 s13, s12, 264
	v_add_u32_e32 v59, s13, v10
	ds_write_b32 v59, v51
	s_add_i32 s12, s46, 30
	s_and_b32 s12, s12, 31
	s_mul_i32 s13, s12, 264
	v_add_u32_e32 v60, s13, v10
	ds_write_b32 v60, v52
	s_add_i32 s12, s46, 31
	s_and_b32 s12, s12, 31
	s_mul_i32 s13, s12, 264
	v_add_u32_e32 v61, s13, v10
	ds_write_b32 v61, v53
; #define LAS __attribute__((address_space(3)))
; __device__ __forceinline__ unsigned pk2(float lo, float hi) { f32x2 v = {lo, hi}; bf16x2_t b = __builtin_convertvector(v, bf16x2_t); return __builtin_bit_cast(unsigned, b); }
; __device__ __forceinline__ void transpose_item(const float* W, int K, int N, bf16* WT, int mode, LAS float* scr, int item, int lane) {
;     const int nblk = N / 32, kb = item / nblk, nb = item % nblk, k0 = 64 * kb, n0 = 32 * nb;
;     const int drow0 = (mode == 0) ? n0 : (mode == 3) ? ((n0 < 2048) ? 256 * (n0 >> 8) + 128 * ((n0 >> 5) & 1) + 32 * ((n0 >> 6) & 3) : n0)
;                                               : (256 * (n0 >> 7) + (n0 & 127) + (mode == 2 ? 128 : 0));
; #pragma unroll 8
;     for (int i = 0; i < 32; ++i) { const int kk = 2 * i + (lane >> 5); scr[kk * 33 + (lane & 31)] = W[(size_t)(k0 + kk) * N + n0 + (lane & 31)]; }
;     asm volatile("s_waitcnt lgkmcnt(0)" ::: "memory");
;     const int c = lane & 7;
; #pragma unroll
;     for (int j = 0; j < 4; ++j) { const int n = (lane >> 3) + 8 * j; const LAS float* s = scr + (8 * c) * 33 + n;
;         u32x4 o; o.x = pk2(s[0 * 33], s[1 * 33]); o.y = pk2(s[2 * 33], s[3 * 33]); o.z = pk2(s[4 * 33], s[5 * 33]); o.w = pk2(s[6 * 33], s[7 * 33]);
;         *(u32x4*)(WT + (size_t)(drow0 + n) * K + k0 + 8 * c) = o; }
;     asm volatile("s_waitcnt lgkmcnt(0)" ::: "memory");
; }
; __global__ void __launch_bounds__(NTHREADS, 2) mega_fwd(Args args) {
;     ...
;             for (int it = gw; it < nitems; it += NGW) transpose_item(W, K, N, dst, mode, scr, it, lane);
.Lp0_np1:
	v_mad_u32_u24 v54, s24, v11, v16
	global_load_dword v22, v54, s[36:37]
	s_add_i32 s12, s24, 1
	s_and_b32 s12, s12, 31
	v_mad_u32_u24 v55, s12, v11, v16
	global_load_dword v23, v55, s[36:37]
	s_add_i32 s12, s24, 2
	s_and_b32 s12, s12, 31
	v_mad_u32_u24 v56, s12, v11, v16
	global_load_dword v24, v56, s[36:37]
	s_add_i32 s12, s24, 3
	s_and_b32 s12, s12, 31
	v_mad_u32_u24 v57, s12, v11, v16
	global_load_dword v25, v57, s[36:37]
	s_add_i32 s12, s24, 4
	s_and_b32 s12, s12, 31
	v_mad_u32_u24 v58, s12, v11, v16
	global_load_dword v26, v58, s[36:37]
	s_add_i32 s12, s24, 5
	s_and_b32 s12, s12, 31
	v_mad_u32_u24 v59, s12, v11, v16
	global_load_dword v27, v59, s[36:37]
	s_add_i32 s12, s24, 6
	s_and_b32 s12, s12, 31
	v_mad_u32_u24 v60, s12, v11, v16
	global_load_dword v28, v60, s[36:37]
	s_add_i32 s12, s24, 7
	s_and_b32 s12, s12, 31
	v_mad_u32_u24 v61, s12, v11, v16
	global_load_dword v29, v61, s[36:37]
	s_add_i32 s12, s24, 8
	s_and_b32 s12, s12, 31
	v_mad_u32_u24 v54, s12, v11, v16
	global_load_dword v30, v54, s[36:37]
	s_add_i32 s12, s24, 9
	s_and_b32 s12, s12, 31
	v_mad_u32_u24 v55, s12, v11, v16
	global_load_dword v31, v55, s[36:37]
	s_add_i32 s12, s24, 10
	s_and_b32 s12, s12, 31
	v_mad_u32_u24 v56, s12, v11, v16
	global_load_dword v32, v56, s[36:37]
	s_add_i32 s12, s24, 11
	s_and_b32 s12, s12, 31
	v_mad_u32_u24 v57, s12, v11, v16
	global_load_dword v33, v57, s[36:37]
	s_add_i32 s12, s24, 12
	s_and_b32 s12, s12, 31
	v_mad_u32_u24 v58, s12, v11, v16
	global_load_dword v34, v58, s[36:37]
	s_add_i32 s12, s24, 13
	s_and_b32 s12, s12, 31
	v_mad_u32_u24 v59, s12, v11, v16
	global_load_dword v35, v59, s[36:37]
	s_add_i32 s12, s24, 14
	s_and_b32 s12, s12, 31
	v_mad_u32_u24 v60, s12, v11, v16
	global_load_dword v36, v60, s[36:37]
	s_add_i32 s12, s24, 15
	s_and_b32 s12, s12, 31
	v_mad_u32_u24 v61, s12, v11, v16
	global_load_dword v37, v61, s[36:37]
	s_add_i32 s12, s24, 16
	s_and_b32 s12, s12, 31
	v_mad_u32_u24 v54, s12, v11, v16
	global_load_dword v38, v54, s[36:37]
	s_add_i32 s12, s24, 17
	s_and_b32 s12, s12, 31
	v_mad_u32_u24 v55, s12, v11, v16
	global_load_dword v39, v55, s[36:37]
	s_add_i32 s12, s24, 18
	s_and_b32 s12, s12, 31
	v_mad_u32_u24 v56, s12, v11, v16
	global_load_dword v40, v56, s[36:37]
	s_add_i32 s12, s24, 19
	s_and_b32 s12, s12, 31
	v_mad_u32_u24 v57, s12, v11, v16
	global_load_dword v41, v57, s[36:37]
	s_add_i32 s12, s24, 20
	s_and_b32 s12, s12, 31
	v_mad_u32_u24 v58, s12, v11, v16
	global_load_dword v42, v58, s[36:37]
	s_add_i32 s12, s24, 21
	s_and_b32 s12, s12, 31
	v_mad_u32_u24 v59, s12, v11, v16
	global_load_dword v43, v59, s[36:37]
	s_add_i32 s12, s24, 22
	s_and_b32 s12, s12, 31
	v_mad_u32_u24 v60, s12, v11, v16
	global_load_dword v44, v60, s[36:37]
	s_add_i32 s12, s24, 23
	s_and_b32 s12, s12, 31
	v_mad_u32_u24 v61, s12, v11, v16
	global_load_dword v45, v61, s[36:37]
	s_add_i32 s12, s24, 24
	s_and_b32 s12, s12, 31
	v_mad_u32_u24 v54, s12, v11, v16
	global_load_dword v46, v54, s[36:37]
	s_add_i32 s12, s24, 25
	s_and_b32 s12, s12, 31
	v_mad_u32_u24 v55, s12, v11, v16
	global_load_dword v47, v55, s[36:37]
	s_add_i32 s12, s24, 26
	s_and_b32 s12, s12, 31
	v_mad_u32_u24 v56, s12, v11, v16
	global_load_dword v48, v56, s[36:37]
	s_add_i32 s12, s24, 27
	s_and_b32 s12, s12, 31
	v_mad_u32_u24 v57, s12, v11, v16
	global_load_dword v49, v57, s[36:37]
	s_add_i32 s12, s24, 28
	s_and_b32 s12, s12, 31
	v_mad_u32_u24 v58, s12, v11, v16
	global_load_dword v50, v58, s[36:37]
	s_add_i32 s12, s24, 29
	s_and_b32 s12, s12, 31
	v_mad_u32_u24 v59, s12, v11, v16
	global_load_dword v51, v59, s[36:37]
	s_add_i32 s12, s24, 30
	s_and_b32 s12, s12, 31
	v_mad_u32_u24 v60, s12, v11, v16
	global_load_dword v52, v60, s[36:37]
	s_add_i32 s12, s24, 31
	s_and_b32 s12, s12, 31
	v_mad_u32_u24 v61, s12, v11, v16
	global_load_dword v53, v61, s[36:37]
	s_cmp_eq_u32 s30, 0
	s_cbranch_scc1 .Lp0_np2
	s_lshl_b32 s13, s31, 4
	s_add_u32 s36, s32, s13
	s_addc_u32 s37, s33, 0
	s_add_u32 s38, s36, s13
	s_addc_u32 s39, s37, 0
	s_add_u32 s40, s38, s13
	s_addc_u32 s41, s39, 0
	v_mul_u32_u24_e32 v9, s31, v7
	v_lshl_add_u32 v9, v9, 1, v8
	s_waitcnt lgkmcnt(0)
	ds_read2_b32 v[62:63], v18 offset0:0 offset1:8
	ds_read2_b32 v[64:65], v18 offset0:33 offset1:41
	ds_read2_b32 v[66:67], v18 offset0:66 offset1:74
	ds_read2_b32 v[68:69], v18 offset0:99 offset1:107
	ds_read2_b32 v[70:71], v18 offset0:132 offset1:140
	ds_read2_b32 v[72:73], v18 offset0:165 offset1:173
	ds_read2_b32 v[74:75], v18 offset0:198 offset1:206
	ds_read2_b32 v[76:77], v18 offset0:231 offset1:239
	s_waitcnt lgkmcnt(6)
	v_cvt_pk_bf16_f32 v78, v62, v64
	s_waitcnt lgkmcnt(4)
	v_cvt_pk_bf16_f32 v79, v66, v68
	s_waitcnt lgkmcnt(2)
	v_cvt_pk_bf16_f32 v80, v70, v72
	s_waitcnt lgkmcnt(0)
	v_cvt_pk_bf16_f32 v81, v74, v76
	global_store_dwordx4 v9, v[78:81], s[32:33]
	v_cvt_pk_bf16_f32 v12, v63, v65
	v_cvt_pk_bf16_f32 v13, v67, v69
	v_cvt_pk_bf16_f32 v14, v71, v73
	v_cvt_pk_bf16_f32 v15, v75, v77
	global_store_dwordx4 v9, v[12:15], s[36:37]
	ds_read2_b32 v[62:63], v18 offset0:16 offset1:24
	ds_read2_b32 v[64:65], v18 offset0:49 offset1:57
	ds_read2_b32 v[66:67], v18 offset0:82 offset1:90
	ds_read2_b32 v[68:69], v18 offset0:115 offset1:123
	ds_read2_b32 v[70:71], v18 offset0:148 offset1:156
	ds_read2_b32 v[72:73], v18 offset0:181 offset1:189
	ds_read2_b32 v[74:75], v18 offset0:214 offset1:222
	ds_read2_b32 v[76:77], v18 offset0:247 offset1:255
	s_waitcnt lgkmcnt(6)
	v_cvt_pk_bf16_f32 v78, v62, v64
	s_waitcnt lgkmcnt(4)
	v_cvt_pk_bf16_f32 v79, v66, v68
	s_waitcnt lgkmcnt(2)
	v_cvt_pk_bf16_f32 v80, v70, v72
	s_waitcnt lgkmcnt(0)
	v_cvt_pk_bf16_f32 v81, v74, v76
	global_store_dwordx4 v9, v[78:81], s[38:39]
	v_cvt_pk_bf16_f32 v12, v63, v65
	v_cvt_pk_bf16_f32 v13, v67, v69
	v_cvt_pk_bf16_f32 v14, v71, v73
	v_cvt_pk_bf16_f32 v15, v75, v77
	global_store_dwordx4 v9, v[12:15], s[40:41]
.Lp0_np2:
	s_mul_i32 s12, s27, s4
	s_add_i32 s12, s12, s29
	s_lshl_b32 s12, s12, 1
	s_add_u32 s32, s34, s12
	s_addc_u32 s33, s35, 0
	s_mov_b32 s31, s4
	s_mov_b32 s46, s24
	s_mov_b32 s30, 1
	s_add_i32 s98, s98, s99
	s_cmp_lt_i32 s98, s21
	s_cbranch_scc1 .Lp0_item
.Lp0_skip:
	s_sub_i32 s98, s98, s21
	s_branch .LBB0_19

; #define LAS __attribute__((address_space(3)))
; __device__ __forceinline__ unsigned pk2(float lo, float hi) { f32x2 v = {lo, hi}; bf16x2_t b = __builtin_convertvector(v, bf16x2_t); return __builtin_bit_cast(unsigned, b); }
; __device__ __forceinline__ void transpose_item(const float* W, int K, int N, bf16* WT, int mode, LAS float* scr, int item, int lane) {
;     const int nblk = N / 32, kb = item / nblk, nb = item % nblk, k0 = 64 * kb, n0 = 32 * nb;
;     const int drow0 = (mode == 0) ? n0 : (mode == 3) ? ((n0 < 2048) ? 256 * (n0 >> 8) + 128 * ((n0 >> 5) & 1) + 32 * ((n0 >> 6) & 3) : n0)
;                                               : (256 * (n0 >> 7) + (n0 & 127) + (mode == 2 ? 128 : 0));
; #pragma unroll 8
;     for (int i = 0; i < 32; ++i) { const int kk = 2 * i + (lane >> 5); scr[kk * 33 + (lane & 31)] = W[(size_t)(k0 + kk) * N + n0 + (lane & 31)]; }
;     asm volatile("s_waitcnt lgkmcnt(0)" ::: "memory");
;     const int c = lane & 7;
; #pragma unroll
;     for (int j = 0; j < 4; ++j) { const int n = (lane >> 3) + 8 * j; const LAS float* s = scr + (8 * c) * 33 + n;
;         u32x4 o; o.x = pk2(s[0 * 33], s[1 * 33]); o.y = pk2(s[2 * 33], s[3 * 33]); o.z = pk2(s[4 * 33], s[5 * 33]); o.w = pk2(s[6 * 33], s[7 * 33]);
;         *(u32x4*)(WT + (size_t)(drow0 + n) * K + k0 + 8 * c) = o; }
;     asm volatile("s_waitcnt lgkmcnt(0)" ::: "memory");
; }
.LBB0_75:
	s_cmp_eq_u32 s30, 0
	s_cbranch_scc1 .Lp0_nflush
	s_waitcnt vmcnt(0)
	s_mul_i32 s13, s46, 264
	v_add_u32_e32 v54, s13, v10
	ds_write_b32 v54, v22
	s_add_i32 s12, s46, 1
	s_and_b32 s12, s12, 31
	s_mul_i32 s13, s12, 264
	v_add_u32_e32 v55, s13, v10
	ds_write_b32 v55, v23
	s_add_i32 s12, s46, 2
	s_and_b32 s12, s12, 31
	s_mul_i32 s13, s12, 264
	v_add_u32_e32 v56, s13, v10
	ds_write_b32 v56, v24
	s_add_i32 s12, s46, 3
	s_and_b32 s12, s12, 31
	s_mul_i32 s13, s12, 264
	v_add_u32_e32 v57, s13, v10
	ds_write_b32 v57, v25
	s_add_i32 s12, s46, 4
	s_and_b32 s12, s12, 31
	s_mul_i32 s13, s12, 264
	v_add_u32_e32 v58, s13, v10
	ds_write_b32 v58, v26
	s_add_i32 s12, s46, 5
	s_and_b32 s12, s12, 31
	s_mul_i32 s13, s12, 264
	v_add_u32_e32 v59, s13, v10
	ds_write_b32 v59, v27
	s_add_i32 s12, s46, 6
	s_and_b32 s12, s12, 31
	s_mul_i32 s13, s12, 264
	v_add_u32_e32 v60, s13, v10
	ds_write_b32 v60, v28
	s_add_i32 s12, s46, 7
	s_and_b32 s12, s12, 31
	s_mul_i32 s13, s12, 264
	v_add_u32_e32 v61, s13, v10
	ds_write_b32 v61, v29
	s_add_i32 s12, s46, 8
	s_and_b32 s12, s12, 31
	s_mul_i32 s13, s12, 264
	v_add_u32_e32 v54, s13, v10
	ds_write_b32 v54, v30
	s_add_i32 s12, s46, 9
	s_and_b32 s12, s12, 31
	s_mul_i32 s13, s12, 264
	v_add_u32_e32 v55, s13, v10
	ds_write_b32 v55, v31
	s_add_i32 s12, s46, 10
	s_and_b32 s12, s12, 31
	s_mul_i32 s13, s12, 264
	v_add_u32_e32 v56, s13, v10
	ds_write_b32 v56, v32
	s_add_i32 s12, s46, 11
	s_and_b32 s12, s12, 31
	s_mul_i32 s13, s12, 264
	v_add_u32_e32 v57, s13, v10
	ds_write_b32 v57, v33
	s_add_i32 s12, s46, 12
	s_and_b32 s12, s12, 31
	s_mul_i32 s13, s12, 264
	v_add_u32_e32 v58, s13, v10
	ds_write_b32 v58, v34
	s_add_i32 s12, s46, 13
	s_and_b32 s12, s12, 31
	s_mul_i32 s13, s12, 264
	v_add_u32_e32 v59, s13, v10
	ds_write_b32 v59, v35
	s_add_i32 s12, s46, 14
	s_and_b32 s12, s12, 31
	s_mul_i32 s13, s12, 264
	v_add_u32_e32 v60, s13, v10
	ds_write_b32 v60, v36
	s_add_i32 s12, s46, 15
	s_and_b32 s12, s12, 31
	s_mul_i32 s13, s12, 264
	v_add_u32_e32 v61, s13, v10
	ds_write_b32 v61, v37
	s_add_i32 s12, s46, 16
	s_and_b32 s12, s12, 31
	s_mul_i32 s13, s12, 264
	v_add_u32_e32 v54, s13, v10
	ds_write_b32 v54, v38
	s_add_i32 s12, s46, 17
	s_and_b32 s12, s12, 31
	s_mul_i32 s13, s12, 264
	v_add_u32_e32 v55, s13, v10
	ds_write_b32 v55, v39
	s_add_i32 s12, s46, 18
	s_and_b32 s12, s12, 31
	s_mul_i32 s13, s12, 264
	v_add_u32_e32 v56, s13, v10
	ds_write_b32 v56, v40
	s_add_i32 s12, s46, 19
	s_and_b32 s12, s12, 31
	s_mul_i32 s13, s12, 264
	v_add_u32_e32 v57, s13, v10
	ds_write_b32 v57, v41
	s_add_i32 s12, s46, 20
	s_and_b32 s12, s12, 31
	s_mul_i32 s13, s12, 264
	v_add_u32_e32 v58, s13, v10
	ds_write_b32 v58, v42
	s_add_i32 s12, s46, 21
	s_and_b32 s12, s12, 31
	s_mul_i32 s13, s12, 264
	v_add_u32_e32 v59, s13, v10
	ds_write_b32 v59, v43
	s_add_i32 s12, s46, 22
	s_and_b32 s12, s12, 31
	s_mul_i32 s13, s12, 264
	v_add_u32_e32 v60, s13, v10
	ds_write_b32 v60, v44
	s_add_i32 s12, s46, 23
	s_and_b32 s12, s12, 31
	s_mul_i32 s13, s12, 264
	v_add_u32_e32 v61, s13, v10
	ds_write_b32 v61, v45
	s_add_i32 s12, s46, 24
	s_and_b32 s12, s12, 31
	s_mul_i32 s13, s12, 264
	v_add_u32_e32 v54, s13, v10
	ds_write_b32 v54, v46
	s_add_i32 s12, s46, 25
	s_and_b32 s12, s12, 31
	s_mul_i32 s13, s12, 264
	v_add_u32_e32 v55, s13, v10
	ds_write_b32 v55, v47
	s_add_i32 s12, s46, 26
	s_and_b32 s12, s12, 31
	s_mul_i32 s13, s12, 264
	v_add_u32_e32 v56, s13, v10
	ds_write_b32 v56, v48
	s_add_i32 s12, s46, 27
	s_and_b32 s12, s12, 31
	s_mul_i32 s13, s12, 264
	v_add_u32_e32 v57, s13, v10
	ds_write_b32 v57, v49
	s_add_i32 s12, s46, 28
	s_and_b32 s12, s12, 31
	s_mul_i32 s13, s12, 264
	v_add_u32_e32 v58, s13, v10
	ds_write_b32 v58, v50
	s_add_i32 s12, s46, 29
	s_and_b32 s12, s12, 31
	s_mul_i32 s13, s12, 264
	v_add_u32_e32 v59, s13, v10
	ds_write_b32 v59, v51
	s_add_i32 s12, s46, 30
	s_and_b32 s12, s12, 31
	s_mul_i32 s13, s12, 264
	v_add_u32_e32 v60, s13, v10
	ds_write_b32 v60, v52
	s_add_i32 s12, s46, 31
	s_and_b32 s12, s12, 31
	s_mul_i32 s13, s12, 264
	v_add_u32_e32 v61, s13, v10
	ds_write_b32 v61, v53
	s_lshl_b32 s13, s31, 4
	s_add_u32 s36, s32, s13
	s_addc_u32 s37, s33, 0
	s_add_u32 s38, s36, s13
	s_addc_u32 s39, s37, 0
	s_add_u32 s40, s38, s13
	s_addc_u32 s41, s39, 0
	v_mul_u32_u24_e32 v9, s31, v7
	v_lshl_add_u32 v9, v9, 1, v8
	s_waitcnt lgkmcnt(0)
	ds_read2_b32 v[62:63], v18 offset0:0 offset1:8
	ds_read2_b32 v[64:65], v18 offset0:33 offset1:41
	ds_read2_b32 v[66:67], v18 offset0:66 offset1:74
	ds_read2_b32 v[68:69], v18 offset0:99 offset1:107
	ds_read2_b32 v[70:71], v18 offset0:132 offset1:140
	ds_read2_b32 v[72:73], v18 offset0:165 offset1:173
	ds_read2_b32 v[74:75], v18 offset0:198 offset1:206
	ds_read2_b32 v[76:77], v18 offset0:231 offset1:239
	s_waitcnt lgkmcnt(6)
	v_cvt_pk_bf16_f32 v78, v62, v64
	s_waitcnt lgkmcnt(4)
	v_cvt_pk_bf16_f32 v79, v66, v68
	s_waitcnt lgkmcnt(2)
	v_cvt_pk_bf16_f32 v80, v70, v72
	s_waitcnt lgkmcnt(0)
	v_cvt_pk_bf16_f32 v81, v74, v76
	global_store_dwordx4 v9, v[78:81], s[32:33]
	v_cvt_pk_bf16_f32 v12, v63, v65
	v_cvt_pk_bf16_f32 v13, v67, v69
	v_cvt_pk_bf16_f32 v14, v71, v73
	v_cvt_pk_bf16_f32 v15, v75, v77
	global_store_dwordx4 v9, v[12:15], s[36:37]
	ds_read2_b32 v[62:63], v18 offset0:16 offset1:24
	ds_read2_b32 v[64:65], v18 offset0:49 offset1:57
	ds_read2_b32 v[66:67], v18 offset0:82 offset1:90
	ds_read2_b32 v[68:69], v18 offset0:115 offset1:123
	ds_read2_b32 v[70:71], v18 offset0:148 offset1:156
	ds_read2_b32 v[72:73], v18 offset0:181 offset1:189
	ds_read2_b32 v[74:75], v18 offset0:214 offset1:222
	ds_read2_b32 v[76:77], v18 offset0:247 offset1:255
	s_waitcnt lgkmcnt(6)
	v_cvt_pk_bf16_f32 v78, v62, v64
	s_waitcnt lgkmcnt(4)
	v_cvt_pk_bf16_f32 v79, v66, v68
	s_waitcnt lgkmcnt(2)
	v_cvt_pk_bf16_f32 v80, v70, v72
	s_waitcnt lgkmcnt(0)
	v_cvt_pk_bf16_f32 v81, v74, v76
	global_store_dwordx4 v9, v[78:81], s[38:39]
	v_cvt_pk_bf16_f32 v12, v63, v65
	v_cvt_pk_bf16_f32 v13, v67, v69
	v_cvt_pk_bf16_f32 v14, v71, v73
	v_cvt_pk_bf16_f32 v15, v75, v77
	global_store_dwordx4 v9, v[12:15], s[40:41]

; #define ATT_LSTORE(buf) do { LAS unsigned char* b_ = lds + (buf) * BUF; \
;         _Pragma("unroll") for (int i = 0; i < KPT; ++i) { if (KCH % NTHREADS == 0 || tid + i * NTHREADS < KCH) *(LAS u32x4*)(b_ + klo[i]) = kreg[i]; } \
;         _Pragma("unroll") for (int i = 0; i < VPT; ++i) *(LAS u32x4*)(b_ + vlo[i]) = vreg[i]; } while (0)
; template <int DQK, int DV, int FLAGS, int qp, int kp, int vts, int op> ...
;     ...
;     unsigned kgo[KPT], vgo[VPT], klo[KPT], vlo[VPT];
; #pragma unroll
;     for (int i = 0; i < KPT; ++i) { const int c = tid + i * NTHREADS; const int row = c / KC, cc = c % KC; kgo[i] = (unsigned)(row * kp + cc * 8) * 2u; klo[i] = (unsigned)(row * KROW + cc * 16); }
; #pragma unroll
;     for (int i = 0; i < VPT; ++i) { const int c = tid + i * NTHREADS; const int d = c >> 3, cc = c & 7; vgo[i] = (unsigned)(d * vts + cc * 8) * 2u; vlo[i] = (unsigned)(KT_BYTES + d * VROW + cc * 16); }
;     ...
;     ATT_GLOAD((FLAGS & AF_REV) ? kt_hi - 1 : kt_lo); ATT_LSTORE(0);
;     __syncthreads();
; __global__ void __launch_bounds__(NTHREADS, 2) mega_fwd(Args args) {
;     ...
;                     const int qb = 63 - (j >> 5), c = j & 31, h = 7 - (c >> 2), b = (c >> 1) & 1, st = c & 1; const size_t row0 = (size_t)b * SEQ + qb * 256;
;                     const float slope2 = exp2f(-(float)(h + 1)) * LOG2E;
;                     const int q0 = qb * 256, cutkeys = (int)((2.0f * Bq + 152.0f) / slope2) + 1;
;                     const int klo = (q0 - 63 - cutkeys >= 0) ? (q0 - 63 - cutkeys) / 64 + 1 : 0;
;     ...
;                     attn_unit<64, 128, AF_CAUSAL | AF_ALIBI | AF_REV, 1024, 1024, SEQ, 1024>(lds, QDb + row0 * 1024 + (2 * h + st) * 64, KDb + (size_t)b * SEQ * 1024 + (2 * h + st) * 64,
;                                          (const bf16*)(ws + A_VTD) + ((size_t)b * 1024 + h * 128) * SEQ, (bf16*)(ws + (st ? A_O2 : A_O1)) + row0 * 1024 + h * 128, q0, klo, 4 * (qb + 1),
;                                          slope2, 0.f, nullptr, 0.f, 2.0f * Bq < 60.0f);
.LBB0_930:
	s_or_b64 exec, exec, s[6:7]
	v_mov_b32_e32 v0, s12
	s_waitcnt lgkmcnt(0)
	s_barrier
	ds_read_b32 v0, v0
	s_movk_i32 s3, 0x7ff
	s_mov_b64 s[6:7], -1
	s_waitcnt lgkmcnt(0)
	s_barrier
	v_cmp_lt_i32_e32 vcc, s3, v0
	v_readfirstlane_b32 s2, v0
	s_cbranch_vccnz .LBB0_925
	s_bfe_u32 s5, s2, 0x30002
	s_ashr_i32 s11, s2, 5
	s_bfe_u32 s6, s2, 0x10001
	s_and_b32 s4, s2, 1
	s_sub_i32 s2, 8, s5
	v_cvt_f32_ubyte0_e32 v0, s2
	s_mov_b32 s2, 0x42fc0000
	v_cmp_lt_f32_e32 vcc, s2, v0
	s_lshl_b32 s10, s11, 8
	v_readlane_b32 s34, v255, 39
	v_cndmask_b32_e32 v2, 0, v219, vcc
	v_sub_f32_e32 v0, v2, v0
	v_exp_f32_e32 v0, v0
	s_sub_i32 s34, 0x3f00, s10
	s_and_b64 s[2:3], vcc, exec
	s_cselect_b32 s2, 0xffffffc0, 0
	v_ldexp_f32 v0, v0, s2
	v_mul_f32_e32 v14, 0x3fb8aa3b, v0
	v_div_scale_f32 v0, s[2:3], v14, v14, v221
	v_rcp_f32_e32 v2, v0
	v_readlane_b32 s35, v255, 40
	v_readlane_b32 s20, v252, 0
	v_readlane_b32 s21, v252, 1
	v_fma_f32 v3, -v0, v2, 1.0
	v_fmac_f32_e32 v2, v3, v2
	v_div_scale_f32 v3, vcc, v221, v14, v221
	v_mul_f32_e32 v4, v3, v2
	v_fma_f32 v5, -v0, v4, v3
	v_fmac_f32_e32 v4, v5, v2
	v_fma_f32 v0, -v0, v4, v3
	v_div_fmas_f32 v0, v0, v2, v4
	v_div_fixup_f32 v0, v0, v14, v221
	v_cvt_i32_f32_e32 v0, v0
	v_readlane_b32 s18, v252, 24
	v_readlane_b32 s19, v252, 25
	v_mov_b32_e32 v15, v212
	v_readfirstlane_b32 s2, v0
	s_not_b32 s2, s2
	s_sub_i32 s2, s2, s10
	s_addk_i32 s2, 0x3ec1
	s_lshr_b32 s3, s2, 6
	s_not_b32 s3, s3
	s_cmp_gt_i32 s2, -1
	s_cselect_b32 s14, s3, 0
	s_lshl_b32 s7, s6, 24
	s_lshl_b64 s[2:3], s[34:35], 10
	s_add_u32 s2, s2, s7
	s_addc_u32 s3, s3, 0
	s_lshl_b64 s[30:31], s[2:3], 1
	s_add_u32 s2, s20, s30
	s_addc_u32 s3, s21, s31
	s_lshl_b32 s5, s5, 7
	s_xor_b32 s12, s5, 0x380
	s_lshl_b32 s7, s4, 7
	s_lshl_b32 s5, s12, 1
	s_or_b32 s7, s7, s5
	s_add_u32 s8, s2, s7
	s_addc_u32 s9, s3, 0
	s_lshl_b32 s2, s6, 25
	v_readlane_b32 s3, v253, 7
	s_add_u32 s3, s3, s2
	v_readlane_b32 s6, v253, 8
	s_addc_u32 s13, s6, 0
	s_add_u32 s6, s3, s7
	s_addc_u32 s7, s13, 0
	s_add_u32 s2, s18, s2
	s_addc_u32 s3, s19, 0
	s_lshl_b32 s12, s12, 15
	s_add_u32 s18, s2, s12
	s_addc_u32 s19, s3, 0
	v_readfirstlane_b32 s2, v15
	s_ashr_i32 s2, s2, 1
	s_movk_i32 s3, 0xffe0
	v_mov_b32_e32 v0, s2
	v_bfi_b32 v176, s3, v0, v15
	v_ashrrev_i32_e32 v177, 31, v176
	v_ashrrev_i32_e32 v0, 31, v15
	s_lshl_b32 s11, s11, 2
	v_lshlrev_b64 v[2:3], 11, v[176:177]
	v_lshrrev_b32_e32 v0, 29, v0
	v_lshl_add_u64 v[2:3], s[8:9], 0, v[2:3]
	v_add_u32_e32 v0, v15, v0
	s_sub_i32 s8, 0xff, s11
	v_writelane_b32 v255, s34, 39
	s_mov_b32 s9, s35
	v_ashrrev_i32_e32 v21, 3, v0
	v_and_b32_e32 v0, 0xffffff8, v0
	s_lshl_b64 s[12:13], s[8:9], 17
	v_bfe_u32 v17, v15, 5, 1
	v_sub_u32_e32 v4, v15, v0
	s_add_u32 s12, s6, s12
	v_lshlrev_b32_e32 v194, 4, v17
	v_mov_b32_e32 v195, v1
	v_lshlrev_b32_e32 v0, 4, v15
	v_add_u32_e32 v5, 0x200, v15
	v_lshlrev_b32_e32 v4, 4, v4
	s_addc_u32 s13, s7, s13
	s_lshl_b64 s[8:9], s[8:9], 7
	v_and_b32_e32 v20, 0x70, v0
	v_ashrrev_i32_e32 v22, 3, v15
	v_ashrrev_i32_e32 v23, 3, v5
	v_lshl_add_u32 v16, v21, 11, v4
	s_add_u32 s8, s18, s8
	v_lshl_add_u64 v[18:19], v[2:3], 0, v[194:195]
	v_lshl_or_b32 v0, v22, 15, v20
	v_lshl_or_b32 v196, v23, 15, v20
	s_addc_u32 s9, s19, s9
	global_load_dwordx4 v[148:151], v16, s[12:13]
	global_load_dwordx4 v[152:155], v0, s[8:9]
	global_load_dwordx4 v[156:159], v196, s[8:9]
	s_sub_u32 s98, s12, 0x20000
	s_subb_u32 s99, s13, 0
	global_load_dwordx4 v[224:227], v16, s[98:99]
	s_sub_u32 s98, s8, 0x80
	s_subb_u32 s99, s9, 0
	global_load_dwordx4 v[228:231], v0, s[98:99]
	global_load_dwordx4 v[232:235], v196, s[98:99]
	global_load_dwordx4 v[2:5], v[18:19], off
	global_load_dwordx4 v[6:9], v[18:19], off offset:32
	global_load_dwordx4 v[10:13], v[18:19], off offset:64
	global_load_dwordx4 v[144:147], v[18:19], off offset:96
	s_movk_i32 s3, 0x90
	v_and_b32_e32 v18, 63, v15
	v_mad_u64_u32 v[200:201], s[12:13], v22, s3, v[20:21]
	v_mad_u64_u32 v[202:203], s[12:13], v23, s3, v[20:21]
	s_movk_i32 s3, 0xf890
	v_lshlrev_b32_e32 v18, 2, v18
	v_mad_u64_u32 v[204:205], s[12:13], v21, s3, v[16:17]
	s_sub_i32 s3, s14, s11
	v_writelane_b32 v255, s35, 40
	s_mov_b64 s[8:9], -1
	v_add_u32_e32 v21, 0, v204
	s_cmpk_gt_i32 s3, 0xff00
	v_xor_b32_e32 v195, 0x80, v18
	v_readlane_b32 s22, v252, 2
	v_readlane_b32 s23, v252, 3
	v_add_u32_e32 v19, 0, v200
	v_add_u32_e32 v20, 0, v202
	s_waitcnt vmcnt(9)
	ds_write_b128 v21, v[148:151]
	s_waitcnt vmcnt(8)
	ds_write_b128 v19, v[152:155] offset:9216
	s_waitcnt vmcnt(7)
	ds_write_b128 v20, v[156:159] offset:9216
	s_waitcnt lgkmcnt(0)
	s_barrier
	s_cbranch_scc1 .LBB0_933
	v_xor_b32_e32 v80, 0x80, v18
	s_mov_b64 s[8:9], 0
; template <int DQK, int DV, int FLAGS, int qp, int kp, int vts, int op> ...
;     ...
;     f32x16 o[NDB];
; #pragma unroll
;     for (int d = 0; d < NDB; ++d)
; #pragma unroll
;         for (int r = 0; r < 16; ++r) o[d][r] = 0.f;
;     float m = (FLAGS & AF_ROBUST) ? -1e30f : 0.f, l = 0.f;
;     f32x16 negm;
; #pragma unroll
;     for (int r = 0; r < 16; ++r) negm[r] = 0.f;
;     u32x4 kreg[KPT], vreg[VPT];
;     unsigned kgo[KPT], vgo[VPT], klo[KPT], vlo[VPT];
; #pragma unroll
;     for (int i = 0; i < KPT; ++i) { const int c = tid + i * NTHREADS; const int row = c / KC, cc = c % KC; kgo[i] = (unsigned)(row * kp + cc * 8) * 2u; klo[i] = (unsigned)(row * KROW + cc * 16); }
; #pragma unroll
;     for (int i = 0; i < VPT; ++i) { const int c = tid + i * NTHREADS; const int d = c >> 3, cc = c & 7; vgo[i] = (unsigned)(d * vts + cc * 8) * 2u; vlo[i] = (unsigned)(KT_BYTES + d * VROW + cc * 16); }
;     ...
;     ATT_GLOAD((FLAGS & AF_REV) ? kt_hi - 1 : kt_lo); ATT_LSTORE(0);
;     __syncthreads();
;     bool started = false;
;     const int prow = (r32 & ~12) | ((r32 & 4) << 1) | ((r32 & 8) >> 1);
;     const int ntile = kt_hi - kt_lo;
;     for (int it = 0; it < ntile; ++it) {
;         const int t = (FLAGS & AF_REV) ? kt_hi - 1 - it : kt_lo + it;
;         const int cur = it & 1;
;         const bool more = (it + 1 < ntile);
;         const int kv0 = t * 64;
;         bool skip = false;
;         if (FLAGS & AF_CAUSAL) skip = skip || (kv0 > qmax_w);
;         if (FLAGS & AF_WINDOW) skip = skip || (kv0 + 63 < qmin_w - (SWA_W - 1));
;         if (!skip) {
;             const LAS unsigned char* kb = lds + cur * BUF + prow * KROW + 16 * hi;
;             const LAS unsigned char* vb = lds + cur * BUF + KT_BYTES + r32 * VROW + 16 * hi;
;             f32x16 p0, p1;
;             bf16x8 kf[2][4];
; #pragma unroll
;             for (int i = 0; i < 2; ++i) { kf[0][2 * i] = *(const LAS bf16x8*)(kb + i * 32); kf[0][2 * i + 1] = *(const LAS bf16x8*)(kb + 32 * KROW + i * 32); }
;             const int nrel = qpos - kv0 - 8 * hi;
;             if (FLAGS & AF_ALIBI) { const float ab = -slope2 * (float)nrel - ((FLAGS & AF_ROBUST) ? 0.f : m);
; #pragma unroll
;                 for (int r = 0; r < 16; ++r) { const float c = (float)(16 * (r >> 3) + (r & 7)); p0[r] = __builtin_fmaf(slope2, c, ab); p1[r] = __builtin_fmaf(slope2, c + 32.f, ab); }
;     ...
;             for (int c = 0; c < ND0 / 2; ++c) {
.LBB0_933:
	s_andn2_b64 vcc, exec, s[8:9]
	v_lshlrev_b32_e32 v198, 3, v17
	s_cbranch_vccnz .LBB0_923
	v_and_b32_e32 v18, 31, v15
	v_and_b32_e32 v19, 19, v15
	v_lshlrev_b32_e32 v20, 1, v15
	v_lshrrev_b32_e32 v15, 1, v15
	s_and_b32 s8, s2, 0xffffffe0
	v_readlane_b32 s12, v255, 39
	v_and_b32_e32 v20, 8, v20
	v_and_b32_e32 v15, 4, v15
	v_mov_b32_e32 v17, v1
	s_add_i32 s20, s8, s12
	v_or3_b32 v15, v19, v20, v15
	s_addk_i32 s8, 0xff40
	v_mov_b32_e32 v64, v1
	v_mov_b32_e32 v65, v1
	v_mul_u32_u24_e32 v201, 0x90, v15
	v_mul_u32_u24_e32 v203, 0x90, v18
	v_lshl_add_u64 v[206:207], s[6:7], 0, v[16:17]
	v_add_u32_e32 v15, s8, v18
	v_mov_b32_e32 v66, v1
	v_mov_b32_e32 v67, v1
	v_mov_b32_e32 v68, v1
	v_mov_b32_e32 v69, v1
	v_mov_b32_e32 v70, v1
	v_mov_b32_e32 v71, v1
	v_mov_b32_e32 v72, v1
	v_mov_b32_e32 v73, v1
	v_mov_b32_e32 v74, v1
	v_mov_b32_e32 v75, v1
	v_mov_b32_e32 v76, v1
	v_mov_b32_e32 v77, v1
	v_mov_b32_e32 v78, v1
	v_mov_b32_e32 v79, v1
	v_mov_b64_e32 v[48:49], v[64:65]
	v_mov_b64_e32 v[32:33], v[64:65]
	v_mov_b64_e32 v[16:17], v[64:65]
	v_mov_b32_e32 v197, v1
	s_or_b32 s21, s20, 31
	s_add_i32 s2, s3, 0xff
	s_addk_i32 s3, 0x100
	v_mov_b32_e32 v208, v14
	v_mov_b32_e32 v209, v14
	v_mov_b32_e32 v210, v14
	v_mov_b32_e32 v211, v14
	s_sub_i32 s34, 0xfe, s11
	v_sub_u32_e32 v205, v15, v198
	s_sub_i32 s22, 0x3fff, s10
	s_mov_b32 s23, 0
	s_mov_b64 s[36:37], 0
	v_mov_b32_e32 v222, 0
	v_mov_b64_e32 v[50:51], v[66:67]
	v_mov_b64_e32 v[52:53], v[68:69]
	v_mov_b64_e32 v[54:55], v[70:71]
	v_mov_b64_e32 v[56:57], v[72:73]
	v_mov_b64_e32 v[58:59], v[74:75]
	v_mov_b64_e32 v[60:61], v[76:77]
	v_mov_b64_e32 v[62:63], v[78:79]
	v_mov_b64_e32 v[34:35], v[66:67]
	v_mov_b64_e32 v[36:37], v[68:69]
	v_mov_b64_e32 v[38:39], v[70:71]
	v_mov_b64_e32 v[40:41], v[72:73]
	v_mov_b64_e32 v[42:43], v[74:75]
	v_mov_b64_e32 v[44:45], v[76:77]
	v_mov_b64_e32 v[46:47], v[78:79]
	v_mov_b64_e32 v[18:19], v[66:67]
	v_mov_b64_e32 v[20:21], v[68:69]
	v_mov_b64_e32 v[22:23], v[70:71]
	v_mov_b64_e32 v[24:25], v[72:73]
	v_mov_b64_e32 v[26:27], v[74:75]
	v_mov_b64_e32 v[28:29], v[76:77]
	v_mov_b64_e32 v[30:31], v[78:79]
	v_mov_b32_e32 v199, 0
	v_readlane_b32 s13, v255, 40
	s_andn2_b64 vcc, exec, s[40:41]
	s_cbranch_vccnz .Ld_fallback
	s_add_i32 s34, s34, -1
	s_waitcnt vmcnt(0)
	v_add_u32_e32 v248, 0x6c00, v204
	v_add_u32_e32 v249, 0x6c00, v200
	v_add_u32_e32 v250, 0x6c00, v202
	ds_write_b128 v248, v[224:227]
	ds_write_b128 v249, v[228:231] offset:9216
	ds_write_b128 v250, v[232:235] offset:9216
	s_ashr_i32 s35, s34, 31
	s_lshl_b64 s[6:7], s[34:35], 17
	s_lshl_b64 s[10:11], s[34:35], 7
	s_add_u32 s10, s18, s10
	s_addc_u32 s11, s19, s11
	v_lshl_add_u64 v[246:247], v[206:207], 0, s[6:7]
	global_load_dwordx4 v[148:151], v[246:247], off
	v_lshl_add_u64 v[246:247], s[10:11], 0, v[0:1]
	global_load_dwordx4 v[152:155], v[246:247], off
	v_lshl_add_u64 v[246:247], s[10:11], 0, v[196:197]
	global_load_dwordx4 v[156:159], v[246:247], off
	s_add_i32 s34, s34, -1
	s_mov_b32 s8, 0x42000000
	s_mov_b32 s9, 0x42040000
	s_sub_i32 s24, s22, s21
	s_ashr_i32 s24, s24, 6
	s_max_i32 s24, s24, 0
	s_waitcnt lgkmcnt(0)
	s_barrier
	s_cmp_lg_u32 s24, 0
	s_cbranch_scc1 .Ld_noqk0
	v_add_u32_e32 v244, v201, v194
	ds_read_b128 v[160:163], v244 offset:0
	ds_read_b128 v[164:167], v244 offset:32
	ds_read_b128 v[168:171], v244 offset:64
	ds_read_b128 v[172:175], v244 offset:96
	ds_read_b128 v[224:227], v244 offset:4608
	ds_read_b128 v[228:231], v244 offset:4640
	ds_read_b128 v[232:235], v244 offset:4672
	ds_read_b128 v[236:239], v244 offset:4704
	v_cvt_f32_i32_e32 v246, v205
	v_fma_f32 v242, -v14, v246, -v222
	v_mov_b32_e32 v80, v242
	v_add_f32_e32 v81, v14, v242
	v_fma_f32 v82, v14, s62, v242
	v_fma_f32 v83, v14, s63, v242
	v_fma_f32 v84, v14, s64, v242
	v_fma_f32 v85, v14, s65, v242
	v_fma_f32 v86, v14, s66, v242
	v_fma_f32 v87, v14, s67, v242
	v_fma_f32 v88, v14, s68, v242
	v_fma_f32 v89, v14, s69, v242
	v_fma_f32 v90, v14, s70, v242
	v_fma_f32 v91, v14, s71, v242
	v_fma_f32 v92, v14, s72, v242
	v_fma_f32 v93, v14, s73, v242
	v_fma_f32 v94, v14, s76, v242
	v_fma_f32 v95, v14, s77, v242
	v_fma_f32 v96, v14, s8, v242
	v_fma_f32 v97, v14, s9, v242
	v_fma_f32 v98, v14, s96, v242
	v_fma_f32 v99, v14, s97, v242
	v_fma_f32 v100, v14, s94, v242
	v_fma_f32 v101, v14, s95, v242
	v_fma_f32 v102, v14, s92, v242
	v_fma_f32 v103, v14, s93, v242
	v_fma_f32 v104, v14, s90, v242
	v_fma_f32 v105, v14, s91, v242
	v_fma_f32 v106, v14, s88, v242
	v_fma_f32 v107, v14, s89, v242
	v_fma_f32 v108, v14, s86, v242
	v_fma_f32 v109, v14, s87, v242
	v_fma_f32 v110, v14, s78, v242
	v_fma_f32 v111, v14, s79, v242
	s_waitcnt lgkmcnt(0)
	v_mfma_f32_32x32x16_bf16 v[80:95], v[160:163], v[2:5], v[80:95]
	v_mfma_f32_32x32x16_bf16 v[96:111], v[224:227], v[2:5], v[96:111]
	v_mfma_f32_32x32x16_bf16 v[80:95], v[164:167], v[6:9], v[80:95]
	v_mfma_f32_32x32x16_bf16 v[96:111], v[228:231], v[6:9], v[96:111]
	v_mfma_f32_32x32x16_bf16 v[80:95], v[168:171], v[10:13], v[80:95]
	v_mfma_f32_32x32x16_bf16 v[96:111], v[232:235], v[10:13], v[96:111]
	v_mfma_f32_32x32x16_bf16 v[80:95], v[172:175], v[144:147], v[80:95]
	v_mfma_f32_32x32x16_bf16 v[96:111], v[236:239], v[144:147], v[96:111]
